# v5: FF1 bias loads hoisted to unit head (epilogue vmcnt drains removed) + attention output stores widened to dwordx4 via permlane32_swap, on top of v2
# baseline (speedup 1.0000x reference)
.Latt_vskip:
	s_or_b64 exec, exec, s[82:83]
	s_lshl_b32 s54, s87, 2
	s_add_i32 s54, s54, s81
	s_lshl_b32 s94, s54, 7
	s_lshl_b32 s54, s54, 8
	s_mov_b32 s55, s95
	v_or_b32_e32 v194, s0, v174
	v_lshl_add_u64 v[158:159], v[152:153], 0, s[54:55]
	v_lshl_add_u64 v[160:161], v[154:155], 0, s[94:95]
	v_lshl_add_u64 v[162:163], v[156:157], 0, s[54:55]
	v_lshrrev_b32_e32 v248, 2, v223
	v_and_b32_e32 v248, 8, v248
	v_mov_b32_e32 v249, 0
	v_lshl_add_u64 v[162:163], v[162:163], 0, v[248:249]
	s_mov_b32 s1, 0
	s_mov_b32 s86, s72
	v_add_u32_e32 v166, s86, v194
	v_ashrrev_i32_e32 v167, 31, v166
	v_lshlrev_b64 v[164:165], 13, v[166:167]
	v_lshl_add_u64 v[0:1], v[158:159], 0, v[164:165]
	v_lshlrev_b64 v[242:243], 12, v[166:167]
	v_lshl_add_u64 v[242:243], v[160:161], 0, v[242:243]
	global_load_dword v225, v[242:243], off
	global_load_dword v226, v[242:243], off offset:8
	global_load_dword v227, v[242:243], off offset:16
	global_load_dword v228, v[242:243], off offset:24
	global_load_dword v229, v[242:243], off offset:32
	global_load_dword v230, v[242:243], off offset:40
	global_load_dword v231, v[242:243], off offset:48
	global_load_dword v232, v[242:243], off offset:56
	global_load_dword v233, v[242:243], off offset:64
	global_load_dword v234, v[242:243], off offset:72
	global_load_dword v235, v[242:243], off offset:80
	global_load_dword v236, v[242:243], off offset:88
	global_load_dword v237, v[242:243], off offset:96
	global_load_dword v238, v[242:243], off offset:104
	global_load_dword v239, v[242:243], off offset:112
	global_load_dword v240, v[242:243], off offset:120
	global_load_dwordx4 v[28:31], v[0:1], off
	global_load_dwordx4 v[24:27], v[0:1], off offset:32
	global_load_dwordx4 v[20:23], v[0:1], off offset:64
	global_load_dwordx4 v[16:19], v[0:1], off offset:96
	global_load_dwordx4 v[12:15], v[0:1], off offset:128
	global_load_dwordx4 v[8:11], v[0:1], off offset:160
	global_load_dwordx4 v[4:7], v[0:1], off offset:192
	s_nop 0
	global_load_dwordx4 v[0:3], v[0:1], off offset:224
	s_cbranch_vccnz .Latt_cnt
	s_waitcnt vmcnt(0)

.LBB0_434:
	v_max3_f32 v38, v132, v215, v217
	v_max3_f32 v38, v38, v216, v214
	v_max3_f32 v38, v38, v213, v212
	v_max3_f32 v38, v38, v211, v203
	v_max3_f32 v38, v38, v202, v201
	v_max3_f32 v38, v38, v200, v199
	v_max3_f32 v38, v38, v198, v197
	v_max3_f32 v38, v38, v196, v195
	v_max3_f32 v38, v38, v48, v49
	v_max3_f32 v38, v38, v50, v51
	v_max3_f32 v38, v38, v52, v53
	v_max3_f32 v38, v38, v54, v55
	v_max3_f32 v38, v38, v56, v57
	v_max3_f32 v38, v38, v58, v59
	v_max3_f32 v38, v38, v60, v61
	v_max3_f32 v38, v38, v62, v63
	v_max3_f32 v38, v38, v16, v17
	v_max3_f32 v38, v38, v18, v19
	v_max3_f32 v38, v38, v20, v21
	v_max3_f32 v38, v38, v22, v23
	v_max3_f32 v38, v38, v24, v25
	v_max3_f32 v38, v38, v26, v27
	v_max3_f32 v38, v38, v28, v29
	v_max3_f32 v38, v38, v30, v31
	v_max3_f32 v38, v38, v0, v1
	v_max3_f32 v38, v38, v2, v3
	v_max3_f32 v38, v38, v4, v5
	v_max3_f32 v38, v38, v6, v7
	v_max3_f32 v38, v38, v8, v9
	v_max3_f32 v38, v38, v10, v11
	v_cndmask_b32_e64 v32, v96, v193, s[20:21]
	v_max3_f32 v38, v38, v12, v13
	v_cndmask_b32_e64 v71, v193, v97, s[22:23]
	v_cndmask_b32_e64 v74, v32, v96, s[22:23]
	v_max3_f32 v38, v38, v14, v15
	v_cndmask_b32_e64 v70, v98, v193, s[24:25]
	v_cndmask_b32_e64 v69, v99, v193, s[26:27]
	v_max3_f32 v38, v38, v74, v71
	v_cndmask_b32_e64 v66, v100, v193, s[28:29]
	v_cndmask_b32_e64 v64, v101, v193, s[30:31]
	v_max3_f32 v38, v38, v70, v69
	v_cndmask_b32_e64 v46, v102, v193, s[34:35]
	v_cndmask_b32_e64 v45, v103, v193, s[36:37]
	v_max3_f32 v38, v38, v66, v64
	v_cndmask_b32_e64 v42, v104, v193, s[38:39]
	v_cndmask_b32_e64 v40, v105, v193, s[40:41]
	v_max3_f32 v38, v38, v46, v45
	v_cndmask_b32_e64 v37, v106, v193, s[42:43]
	v_cndmask_b32_e64 v36, v107, v193, s[44:45]
	v_max3_f32 v38, v38, v42, v40
	v_cndmask_b32_e64 v35, v108, v193, s[46:47]
	v_cndmask_b32_e64 v34, v109, v193, s[48:49]
	v_max3_f32 v38, v38, v37, v36
	v_cndmask_b32_e64 v33, v110, v193, s[50:51]
	v_cndmask_b32_e64 v32, v111, v193, s[52:53]
	v_max3_f32 v38, v38, v35, v34
	v_max3_f32 v38, v38, v33, v32
	ds_bpermute_b32 v39, v175, v38
	s_cmp_eq_u32 s1, 0
	s_mov_b32 s1, s94
	s_waitcnt lgkmcnt(0)
	v_max_f32_e32 v39, v39, v39
	v_max_f32_e32 v38, v38, v39
	v_sub_f32_e32 v39, v215, v38
	v_exp_f32_e32 v39, v39
	v_sub_f32_e32 v41, v217, v38
	v_exp_f32_e32 v41, v41
	v_sub_f32_e32 v80, v196, v38
	v_add_f32_e32 v43, 0, v39
	v_exp_f32_e32 v80, v80
	v_add_f32_e32 v44, v41, v43
	v_sub_f32_e32 v43, v216, v38
	v_exp_f32_e32 v43, v43
	v_sub_f32_e32 v81, v195, v38
	v_exp_f32_e32 v81, v81
	v_sub_f32_e32 v48, v48, v38
	v_add_f32_e32 v47, v43, v44
	v_sub_f32_e32 v44, v214, v38
	v_exp_f32_e32 v44, v44
	v_exp_f32_e32 v82, v48
	v_sub_f32_e32 v49, v49, v38
	v_sub_f32_e32 v16, v16, v38
	v_add_f32_e32 v65, v44, v47
	v_sub_f32_e32 v47, v213, v38
	v_exp_f32_e32 v47, v47
	v_exp_f32_e32 v16, v16
	v_sub_f32_e32 v17, v17, v38
	v_exp_f32_e32 v17, v17
	v_add_f32_e32 v67, v47, v65
	v_sub_f32_e32 v65, v212, v38
	v_exp_f32_e32 v65, v65
	v_sub_f32_e32 v18, v18, v38
	v_exp_f32_e32 v18, v18
	v_sub_f32_e32 v19, v19, v38
	v_add_f32_e32 v68, v65, v67
	v_sub_f32_e32 v67, v211, v38
	v_exp_f32_e32 v67, v67
	v_exp_f32_e32 v19, v19
	v_sub_f32_e32 v20, v20, v38
	v_exp_f32_e32 v20, v20
	v_add_f32_e32 v72, v67, v68
	v_sub_f32_e32 v68, v203, v38
	v_exp_f32_e32 v68, v68
	v_sub_f32_e32 v21, v21, v38
	v_exp_f32_e32 v21, v21
	v_sub_f32_e32 v22, v22, v38
	v_add_f32_e32 v73, v68, v72
	v_sub_f32_e32 v72, v202, v38
	v_exp_f32_e32 v72, v72
	v_exp_f32_e32 v22, v22
	v_sub_f32_e32 v23, v23, v38
	v_exp_f32_e32 v23, v23
	v_add_f32_e32 v75, v72, v73
	v_sub_f32_e32 v73, v201, v38
	v_exp_f32_e32 v73, v73
	v_sub_f32_e32 v24, v24, v38
	v_exp_f32_e32 v89, v24
	v_sub_f32_e32 v25, v25, v38
	v_add_f32_e32 v76, v73, v75
	v_sub_f32_e32 v75, v200, v38
	v_exp_f32_e32 v75, v75
	v_exp_f32_e32 v90, v25
	v_sub_f32_e32 v25, v26, v38
	v_exp_f32_e32 v91, v25
	v_add_f32_e32 v77, v75, v76
	v_sub_f32_e32 v76, v199, v38
	v_exp_f32_e32 v76, v76
	v_sub_f32_e32 v25, v27, v38
	v_exp_f32_e32 v92, v25
	v_sub_f32_e32 v25, v28, v38
	v_add_f32_e32 v78, v76, v77
	v_sub_f32_e32 v77, v198, v38
	v_exp_f32_e32 v77, v77
	v_exp_f32_e32 v93, v25
	v_sub_f32_e32 v25, v29, v38
	v_exp_f32_e32 v94, v25
	v_add_f32_e32 v79, v77, v78
	v_sub_f32_e32 v78, v197, v38
	v_exp_f32_e32 v78, v78
	v_sub_f32_e32 v25, v30, v38
	v_exp_f32_e32 v95, v25
	v_sub_f32_e32 v25, v31, v38
	v_add_f32_e32 v79, v78, v79
	v_add_f32_e32 v79, v80, v79
	v_add_f32_e32 v79, v81, v79
	v_add_f32_e32 v48, v82, v79
	v_exp_f32_e32 v79, v49
	v_sub_f32_e32 v49, v50, v38
	v_exp_f32_e32 v83, v49
	v_sub_f32_e32 v49, v51, v38
	v_exp_f32_e32 v84, v49
	v_sub_f32_e32 v49, v52, v38
	v_exp_f32_e32 v85, v49
	v_sub_f32_e32 v49, v53, v38
	v_add_f32_e32 v48, v79, v48
	v_exp_f32_e32 v86, v49
	v_sub_f32_e32 v49, v54, v38
	v_add_f32_e32 v48, v83, v48
	v_exp_f32_e32 v87, v49
	v_sub_f32_e32 v49, v55, v38
	v_add_f32_e32 v48, v84, v48
	v_exp_f32_e32 v88, v49
	v_sub_f32_e32 v49, v56, v38
	v_add_f32_e32 v48, v85, v48
	v_exp_f32_e32 v56, v49
	v_sub_f32_e32 v49, v57, v38
	v_add_f32_e32 v48, v86, v48
	v_exp_f32_e32 v57, v49
	v_sub_f32_e32 v49, v58, v38
	v_add_f32_e32 v48, v87, v48
	v_exp_f32_e32 v58, v49
	v_sub_f32_e32 v49, v59, v38
	v_add_f32_e32 v48, v88, v48
	v_exp_f32_e32 v59, v49
	v_sub_f32_e32 v49, v60, v38
	v_add_f32_e32 v48, v56, v48
	v_exp_f32_e32 v60, v49
	v_sub_f32_e32 v49, v61, v38
	v_add_f32_e32 v48, v57, v48
	v_exp_f32_e32 v61, v49
	v_sub_f32_e32 v49, v62, v38
	v_add_f32_e32 v48, v58, v48
	v_exp_f32_e32 v62, v49
	v_sub_f32_e32 v49, v63, v38
	v_add_f32_e32 v48, v59, v48
	v_exp_f32_e32 v63, v49
	v_add_f32_e32 v48, v60, v48
	v_add_f32_e32 v48, v61, v48
	v_add_f32_e32 v48, v62, v48
	v_add_f32_e32 v48, v63, v48
	v_add_f32_e32 v48, v16, v48
	v_add_f32_e32 v48, v17, v48
	v_add_f32_e32 v48, v18, v48
	v_add_f32_e32 v48, v19, v48
	v_add_f32_e32 v48, v20, v48
	v_add_f32_e32 v48, v21, v48
	v_add_f32_e32 v48, v22, v48
	v_add_f32_e32 v48, v23, v48
	v_add_f32_e32 v24, v89, v48
	v_add_f32_e32 v24, v90, v24
	v_add_f32_e32 v24, v91, v24
	v_add_f32_e32 v24, v92, v24
	v_exp_f32_e32 v96, v25
	v_sub_f32_e32 v0, v0, v38
	v_add_f32_e32 v24, v93, v24
	v_exp_f32_e32 v0, v0
	v_sub_f32_e32 v1, v1, v38
	v_add_f32_e32 v24, v94, v24
	v_exp_f32_e32 v1, v1
	v_sub_f32_e32 v2, v2, v38
	v_add_f32_e32 v24, v95, v24
	v_exp_f32_e32 v2, v2
	v_sub_f32_e32 v3, v3, v38
	v_add_f32_e32 v24, v96, v24
	v_exp_f32_e32 v3, v3
	v_sub_f32_e32 v4, v4, v38
	v_add_f32_e32 v24, v0, v24
	v_exp_f32_e32 v4, v4
	v_sub_f32_e32 v5, v5, v38
	v_add_f32_e32 v24, v1, v24
	v_exp_f32_e32 v5, v5
	v_sub_f32_e32 v6, v6, v38
	v_add_f32_e32 v24, v2, v24
	v_exp_f32_e32 v6, v6
	v_sub_f32_e32 v7, v7, v38
	v_add_f32_e32 v24, v3, v24
	v_exp_f32_e32 v7, v7
	v_sub_f32_e32 v8, v8, v38
	v_add_f32_e32 v24, v4, v24
	v_exp_f32_e32 v8, v8
	v_sub_f32_e32 v9, v9, v38
	v_add_f32_e32 v24, v5, v24
	v_exp_f32_e32 v9, v9
	v_sub_f32_e32 v10, v10, v38
	v_add_f32_e32 v24, v6, v24
	v_exp_f32_e32 v10, v10
	v_sub_f32_e32 v11, v11, v38
	v_add_f32_e32 v24, v7, v24
	v_exp_f32_e32 v11, v11
	v_sub_f32_e32 v12, v12, v38
	v_add_f32_e32 v24, v8, v24
	v_exp_f32_e32 v12, v12
	v_sub_f32_e32 v13, v13, v38
	v_add_f32_e32 v24, v9, v24
	v_exp_f32_e32 v13, v13
	v_sub_f32_e32 v14, v14, v38
	v_add_f32_e32 v24, v10, v24
	v_exp_f32_e32 v14, v14
	v_sub_f32_e32 v15, v15, v38
	v_add_f32_e32 v24, v11, v24
	v_exp_f32_e32 v15, v15
	v_sub_f32_e32 v25, v74, v38
	v_add_f32_e32 v24, v12, v24
	v_exp_f32_e32 v74, v25
	v_sub_f32_e32 v25, v71, v38
	v_add_f32_e32 v24, v13, v24
	v_exp_f32_e32 v71, v25
	v_sub_f32_e32 v25, v70, v38
	v_add_f32_e32 v24, v14, v24
	v_exp_f32_e32 v70, v25
	v_sub_f32_e32 v25, v69, v38
	v_add_f32_e32 v24, v15, v24
	v_exp_f32_e32 v69, v25
	v_sub_f32_e32 v25, v66, v38
	v_add_f32_e32 v24, v74, v24
	v_exp_f32_e32 v66, v25
	v_sub_f32_e32 v25, v64, v38
	v_add_f32_e32 v24, v71, v24
	v_exp_f32_e32 v64, v25
	v_sub_f32_e32 v25, v46, v38
	v_add_f32_e32 v24, v70, v24
	v_exp_f32_e32 v97, v25
	v_sub_f32_e32 v25, v45, v38
	v_add_f32_e32 v24, v69, v24
	v_exp_f32_e32 v98, v25
	v_sub_f32_e32 v25, v42, v38
	v_add_f32_e32 v24, v66, v24
	v_exp_f32_e32 v99, v25
	v_sub_f32_e32 v25, v40, v38
	v_add_f32_e32 v24, v64, v24
	v_exp_f32_e32 v100, v25
	v_sub_f32_e32 v25, v37, v38
	v_add_f32_e32 v24, v97, v24
	v_exp_f32_e32 v101, v25
	v_sub_f32_e32 v25, v36, v38
	v_add_f32_e32 v24, v98, v24
	v_exp_f32_e32 v102, v25
	v_sub_f32_e32 v25, v35, v38
	v_add_f32_e32 v24, v99, v24
	v_exp_f32_e32 v103, v25
	v_sub_f32_e32 v25, v34, v38
	v_add_f32_e32 v24, v100, v24
	v_exp_f32_e32 v104, v25
	v_sub_f32_e32 v25, v33, v38
	v_add_f32_e32 v24, v101, v24
	v_exp_f32_e32 v105, v25
	v_sub_f32_e32 v25, v32, v38
	v_add_f32_e32 v24, v102, v24
	v_exp_f32_e32 v106, v25
	v_add_f32_e32 v24, v103, v24
	v_add_f32_e32 v24, v104, v24
	v_add_f32_e32 v24, v105, v24
	v_add_f32_e32 v107, v106, v24
	ds_bpermute_b32 v108, v175, v107
	v_sub_f32_e32 v24, v132, v38
	v_exp_f32_e32 v109, v24
	v_cvt_pk_bf16_f32 v40, v0, v1
	v_cvt_pk_bf16_f32 v48, v39, v41
	s_waitcnt lgkmcnt(0)
	v_add_f32_e32 v0, v107, v108
	v_add_f32_e32 v0, v109, v0
	v_div_scale_f32 v1, s[54:55], v0, v0, s76
	v_cvt_pk_bf16_f32 v41, v2, v3
	v_rcp_f32_e32 v2, v1
	v_cvt_pk_bf16_f32 v42, v4, v5
	v_cvt_pk_bf16_f32 v50, v47, v65
	v_lshl_add_u32 v65, s86, 1, v176
	v_fma_f32 v3, -v1, v2, 1.0
	v_fmac_f32_e32 v2, v3, v2
	v_div_scale_f32 v3, vcc, s76, v0, s76
	v_mul_f32_e32 v4, v3, v2
	v_fma_f32 v5, -v1, v4, v3
	v_fmac_f32_e32 v4, v5, v2
	v_fma_f32 v1, -v1, v4, v3
	v_div_fmas_f32 v1, v1, v2, v4
	v_cvt_pk_bf16_f32 v28, v56, v57
	v_cvt_pk_bf16_f32 v29, v58, v59
	v_cvt_pk_bf16_f32 v35, v22, v23
	v_cvt_pk_bf16_f32 v22, v66, v64
	v_div_fixup_f32 v64, v1, v0, s76
	ds_read2_b64 v[0:3], v65 offset1:2
	ds_read2_b64 v[56:59], v65 offset0:4 offset1:6
	v_cvt_pk_bf16_f32 v49, v43, v44
	v_cvt_pk_bf16_f32 v51, v67, v68
	v_cvt_pk_bf16_f32 v43, v6, v7
	v_cvt_pk_bf16_f32 v44, v8, v9
	v_cvt_pk_bf16_f32 v45, v10, v11
	v_cvt_pk_bf16_f32 v46, v12, v13
	v_cvt_pk_bf16_f32 v47, v14, v15
	s_waitcnt lgkmcnt(1)
	v_mfma_f32_32x32x16_bf16 v[0:15], v[0:3], v[48:51], 0
	v_cvt_pk_bf16_f32 v52, v72, v73
	v_cvt_pk_bf16_f32 v53, v75, v76
	v_cvt_pk_bf16_f32 v54, v77, v78
	v_cvt_pk_bf16_f32 v55, v80, v81
	v_cvt_pk_bf16_f32 v24, v82, v79
	v_cvt_pk_bf16_f32 v25, v83, v84
	v_cvt_pk_bf16_f32 v26, v85, v86
	s_waitcnt lgkmcnt(0)
	v_mfma_f32_32x32x16_bf16 v[0:15], v[56:59], v[52:55], v[0:15]
	ds_read2_b64 v[56:59], v65 offset0:8 offset1:10
	v_cvt_pk_bf16_f32 v27, v87, v88
	v_cvt_pk_bf16_f32 v30, v60, v61
	v_cvt_pk_bf16_f32 v31, v62, v63
	v_cvt_pk_bf16_f32 v32, v16, v17
	v_cvt_pk_bf16_f32 v33, v18, v19
	v_cvt_pk_bf16_f32 v34, v20, v21
	s_waitcnt lgkmcnt(0)
	v_mfma_f32_32x32x16_bf16 v[0:15], v[56:59], v[24:27], v[0:15]
	ds_read2_b64 v[56:59], v65 offset0:12 offset1:14
	v_cvt_pk_bf16_f32 v36, v89, v90
	v_cvt_pk_bf16_f32 v37, v91, v92
	v_cvt_pk_bf16_f32 v38, v93, v94
	v_cvt_pk_bf16_f32 v39, v95, v96
	v_lshlrev_b64 v[66:67], 12, v[166:167]
	v_lshl_add_u64 v[66:67], v[160:161], 0, v[66:67]
	s_waitcnt lgkmcnt(0)
	v_mfma_f32_32x32x16_bf16 v[0:15], v[56:59], v[28:31], v[0:15]
	ds_read2_b64 v[56:59], v65 offset0:16 offset1:18
	v_cvt_pk_bf16_f32 v20, v74, v71
	v_cvt_pk_bf16_f32 v21, v70, v69
	v_cvt_pk_bf16_f32 v23, v97, v98
	v_cvt_pk_bf16_f32 v16, v99, v100
	v_cvt_pk_bf16_f32 v17, v101, v102
	v_cvt_pk_bf16_f32 v18, v103, v104
	s_waitcnt lgkmcnt(0)
	v_mfma_f32_32x32x16_bf16 v[0:15], v[56:59], v[32:35], v[0:15]
	ds_read2_b64 v[56:59], v65 offset0:20 offset1:22
	v_cvt_pk_bf16_f32 v19, v105, v106
	s_waitcnt lgkmcnt(0)
	v_mfma_f32_32x32x16_bf16 v[0:15], v[56:59], v[36:39], v[0:15]
	ds_read2_b64 v[56:59], v65 offset0:24 offset1:26
	s_waitcnt lgkmcnt(0)
	v_mfma_f32_32x32x16_bf16 v[0:15], v[56:59], v[40:43], v[0:15]
	ds_read2_b64 v[56:59], v65 offset0:28 offset1:30
	s_waitcnt lgkmcnt(0)
	v_mfma_f32_32x32x16_bf16 v[0:15], v[56:59], v[44:47], v[0:15]
	ds_read2_b64 v[60:63], v65 offset0:32 offset1:34
	ds_read2_b64 v[56:59], v65 offset0:36 offset1:38
	s_waitcnt lgkmcnt(1)
	v_mfma_f32_32x32x16_bf16 v[0:15], v[60:63], v[20:23], v[0:15]
	v_add_u32_e32 v62, 0x4000, v65
	s_waitcnt lgkmcnt(0)
	v_mfma_f32_32x32x16_bf16 v[0:15], v[56:59], v[16:19], v[0:15]
	v_lshl_add_u64 v[56:57], v[162:163], 0, v[164:165]
	v_cvt_f32_ubyte1_e32 v249, v225
	v_cvt_f32_ubyte0_e32 v248, v225
	s_nop 9
	v_pk_mul_f32 v[0:1], v[0:1], v[64:65] op_sel_hi:[1,0]
	v_pk_mul_f32 v[0:1], v[0:1], v[248:249]
	v_cvt_f32_ubyte3_e32 v249, v225
	v_cvt_f32_ubyte2_e32 v248, v225
	v_pk_mul_f32 v[2:3], v[2:3], v[64:65] op_sel_hi:[1,0]
	v_pk_mul_f32 v[2:3], v[2:3], v[248:249]
	v_cvt_f32_ubyte1_e32 v249, v226
	v_cvt_f32_ubyte0_e32 v248, v226
	v_pk_mul_f32 v[4:5], v[4:5], v[64:65] op_sel_hi:[1,0]
	v_pk_mul_f32 v[4:5], v[4:5], v[248:249]
	v_cvt_f32_ubyte3_e32 v249, v226
	v_cvt_f32_ubyte2_e32 v248, v226
	v_pk_mul_f32 v[6:7], v[6:7], v[64:65] op_sel_hi:[1,0]
	v_pk_mul_f32 v[6:7], v[6:7], v[248:249]
	v_cvt_pk_bf16_f32 v0, v0, v1
	v_cvt_pk_bf16_f32 v1, v2, v3
	v_cvt_pk_bf16_f32 v2, v4, v5
	v_cvt_pk_bf16_f32 v3, v6, v7
	s_nop 1
	v_permlane32_swap_b32_e32 v0, v2
	v_permlane32_swap_b32_e32 v1, v3
	global_store_dwordx4 v[56:57], v[0:3], off
	v_cvt_f32_ubyte1_e32 v249, v227
	v_cvt_f32_ubyte0_e32 v248, v227
	v_pk_mul_f32 v[8:9], v[8:9], v[64:65] op_sel_hi:[1,0]
	v_pk_mul_f32 v[8:9], v[8:9], v[248:249]
	v_cvt_f32_ubyte3_e32 v249, v227
	v_cvt_f32_ubyte2_e32 v248, v227
	v_pk_mul_f32 v[10:11], v[10:11], v[64:65] op_sel_hi:[1,0]
	v_pk_mul_f32 v[10:11], v[10:11], v[248:249]
	v_cvt_f32_ubyte1_e32 v249, v228
	v_cvt_f32_ubyte0_e32 v248, v228
	v_pk_mul_f32 v[12:13], v[12:13], v[64:65] op_sel_hi:[1,0]
	v_pk_mul_f32 v[12:13], v[12:13], v[248:249]
	v_cvt_f32_ubyte3_e32 v249, v228
	v_cvt_f32_ubyte2_e32 v248, v228
	v_pk_mul_f32 v[14:15], v[14:15], v[64:65] op_sel_hi:[1,0]
	v_pk_mul_f32 v[14:15], v[14:15], v[248:249]
	v_cvt_pk_bf16_f32 v8, v8, v9
	v_cvt_pk_bf16_f32 v9, v10, v11
	v_cvt_pk_bf16_f32 v10, v12, v13
	v_cvt_pk_bf16_f32 v11, v14, v15
	s_nop 1
	v_permlane32_swap_b32_e32 v8, v10
	v_permlane32_swap_b32_e32 v9, v11
	global_store_dwordx4 v[56:57], v[8:11], off offset:32
	ds_read2_b64 v[0:3], v62 offset0:32 offset1:34
	ds_read2_b64 v[58:61], v62 offset0:36 offset1:38
	s_waitcnt lgkmcnt(1)
	v_mfma_f32_32x32x16_bf16 v[0:15], v[0:3], v[48:51], 0
	s_waitcnt lgkmcnt(0)
	v_mfma_f32_32x32x16_bf16 v[0:15], v[58:61], v[52:55], v[0:15]
	ds_read2_b64 v[58:61], v62 offset0:40 offset1:42
	s_waitcnt lgkmcnt(0)
	v_mfma_f32_32x32x16_bf16 v[0:15], v[58:61], v[24:27], v[0:15]
	ds_read2_b64 v[58:61], v62 offset0:44 offset1:46
	s_waitcnt lgkmcnt(0)
	v_mfma_f32_32x32x16_bf16 v[0:15], v[58:61], v[28:31], v[0:15]
	ds_read2_b64 v[58:61], v62 offset0:48 offset1:50
	s_waitcnt lgkmcnt(0)
	v_mfma_f32_32x32x16_bf16 v[0:15], v[58:61], v[32:35], v[0:15]
	ds_read2_b64 v[58:61], v62 offset0:52 offset1:54
	s_waitcnt lgkmcnt(0)
	v_mfma_f32_32x32x16_bf16 v[0:15], v[58:61], v[36:39], v[0:15]
	ds_read2_b64 v[58:61], v62 offset0:56 offset1:58
	s_waitcnt lgkmcnt(0)
	v_mfma_f32_32x32x16_bf16 v[0:15], v[58:61], v[40:43], v[0:15]
	ds_read2_b64 v[58:61], v62 offset0:60 offset1:62
	s_waitcnt lgkmcnt(0)
	v_mfma_f32_32x32x16_bf16 v[0:15], v[58:61], v[44:47], v[0:15]
	ds_read2_b64 v[58:61], v62 offset0:64 offset1:66
	ds_read2_b64 v[68:71], v62 offset0:68 offset1:70
	s_waitcnt lgkmcnt(1)
	v_mfma_f32_32x32x16_bf16 v[0:15], v[58:61], v[20:23], v[0:15]
	s_nop 0
	v_cvt_f32_ubyte1_e32 v59, v229
	s_waitcnt lgkmcnt(0)
	v_mfma_f32_32x32x16_bf16 v[0:15], v[68:71], v[16:19], v[0:15]
	v_cvt_f32_ubyte1_e32 v249, v229
	v_cvt_f32_ubyte0_e32 v248, v229
	s_nop 9
	v_pk_mul_f32 v[0:1], v[0:1], v[64:65] op_sel_hi:[1,0]
	v_pk_mul_f32 v[0:1], v[0:1], v[248:249]
	v_cvt_f32_ubyte3_e32 v249, v229
	v_cvt_f32_ubyte2_e32 v248, v229
	v_pk_mul_f32 v[2:3], v[2:3], v[64:65] op_sel_hi:[1,0]
	v_pk_mul_f32 v[2:3], v[2:3], v[248:249]
	v_cvt_f32_ubyte1_e32 v249, v230
	v_cvt_f32_ubyte0_e32 v248, v230
	v_pk_mul_f32 v[4:5], v[4:5], v[64:65] op_sel_hi:[1,0]
	v_pk_mul_f32 v[4:5], v[4:5], v[248:249]
	v_cvt_f32_ubyte3_e32 v249, v230
	v_cvt_f32_ubyte2_e32 v248, v230
	v_pk_mul_f32 v[6:7], v[6:7], v[64:65] op_sel_hi:[1,0]
	v_pk_mul_f32 v[6:7], v[6:7], v[248:249]
	v_cvt_pk_bf16_f32 v0, v0, v1
	v_cvt_pk_bf16_f32 v1, v2, v3
	v_cvt_pk_bf16_f32 v2, v4, v5
	v_cvt_pk_bf16_f32 v3, v6, v7
	s_nop 1
	v_permlane32_swap_b32_e32 v0, v2
	v_permlane32_swap_b32_e32 v1, v3
	global_store_dwordx4 v[56:57], v[0:3], off offset:64
	v_cvt_f32_ubyte1_e32 v249, v231
	v_cvt_f32_ubyte0_e32 v248, v231
	v_pk_mul_f32 v[8:9], v[8:9], v[64:65] op_sel_hi:[1,0]
	v_pk_mul_f32 v[8:9], v[8:9], v[248:249]
	v_cvt_f32_ubyte3_e32 v249, v231
	v_cvt_f32_ubyte2_e32 v248, v231
	v_pk_mul_f32 v[10:11], v[10:11], v[64:65] op_sel_hi:[1,0]
	v_pk_mul_f32 v[10:11], v[10:11], v[248:249]
	v_cvt_f32_ubyte1_e32 v249, v232
	v_cvt_f32_ubyte0_e32 v248, v232
	v_pk_mul_f32 v[12:13], v[12:13], v[64:65] op_sel_hi:[1,0]
	v_pk_mul_f32 v[12:13], v[12:13], v[248:249]
	v_cvt_f32_ubyte3_e32 v249, v232
	v_cvt_f32_ubyte2_e32 v248, v232
	v_pk_mul_f32 v[14:15], v[14:15], v[64:65] op_sel_hi:[1,0]
	v_pk_mul_f32 v[14:15], v[14:15], v[248:249]
	v_cvt_pk_bf16_f32 v8, v8, v9
	v_cvt_pk_bf16_f32 v9, v10, v11
	v_cvt_pk_bf16_f32 v10, v12, v13
	v_cvt_pk_bf16_f32 v11, v14, v15
	s_nop 1
	v_permlane32_swap_b32_e32 v8, v10
	v_permlane32_swap_b32_e32 v9, v11
	global_store_dwordx4 v[56:57], v[8:11], off offset:96
	v_add_u32_e32 v62, 0x8000, v65
	ds_read2_b64 v[0:3], v62 offset0:64 offset1:66
	ds_read2_b64 v[58:61], v62 offset0:68 offset1:70
	s_waitcnt lgkmcnt(1)
	v_mfma_f32_32x32x16_bf16 v[0:15], v[0:3], v[48:51], 0
	s_waitcnt lgkmcnt(0)
	v_mfma_f32_32x32x16_bf16 v[0:15], v[58:61], v[52:55], v[0:15]
	ds_read2_b64 v[58:61], v62 offset0:72 offset1:74
	s_waitcnt lgkmcnt(0)
	v_mfma_f32_32x32x16_bf16 v[0:15], v[58:61], v[24:27], v[0:15]
	ds_read2_b64 v[58:61], v62 offset0:76 offset1:78
	s_waitcnt lgkmcnt(0)
	v_mfma_f32_32x32x16_bf16 v[0:15], v[58:61], v[28:31], v[0:15]
	ds_read2_b64 v[58:61], v62 offset0:80 offset1:82
	s_waitcnt lgkmcnt(0)
	v_mfma_f32_32x32x16_bf16 v[0:15], v[58:61], v[32:35], v[0:15]
	ds_read2_b64 v[58:61], v62 offset0:84 offset1:86
	s_waitcnt lgkmcnt(0)
	v_mfma_f32_32x32x16_bf16 v[0:15], v[58:61], v[36:39], v[0:15]
	ds_read2_b64 v[58:61], v62 offset0:88 offset1:90
	s_waitcnt lgkmcnt(0)
	v_mfma_f32_32x32x16_bf16 v[0:15], v[58:61], v[40:43], v[0:15]
	ds_read2_b64 v[58:61], v62 offset0:92 offset1:94
	s_waitcnt lgkmcnt(0)
	v_mfma_f32_32x32x16_bf16 v[0:15], v[58:61], v[44:47], v[0:15]
	ds_read2_b64 v[58:61], v62 offset0:96 offset1:98
	ds_read2_b64 v[68:71], v62 offset0:100 offset1:102
	s_waitcnt lgkmcnt(1)
	v_mfma_f32_32x32x16_bf16 v[0:15], v[58:61], v[20:23], v[0:15]
	s_nop 0
	v_cvt_f32_ubyte1_e32 v59, v233
	s_waitcnt lgkmcnt(0)
	v_mfma_f32_32x32x16_bf16 v[0:15], v[68:71], v[16:19], v[0:15]
	v_cvt_f32_ubyte1_e32 v249, v233
	v_cvt_f32_ubyte0_e32 v248, v233
	s_nop 9
	v_pk_mul_f32 v[0:1], v[0:1], v[64:65] op_sel_hi:[1,0]
	v_pk_mul_f32 v[0:1], v[0:1], v[248:249]
	v_cvt_f32_ubyte3_e32 v249, v233
	v_cvt_f32_ubyte2_e32 v248, v233
	v_pk_mul_f32 v[2:3], v[2:3], v[64:65] op_sel_hi:[1,0]
	v_pk_mul_f32 v[2:3], v[2:3], v[248:249]
	v_cvt_f32_ubyte1_e32 v249, v234
	v_cvt_f32_ubyte0_e32 v248, v234
	v_pk_mul_f32 v[4:5], v[4:5], v[64:65] op_sel_hi:[1,0]
	v_pk_mul_f32 v[4:5], v[4:5], v[248:249]
	v_cvt_f32_ubyte3_e32 v249, v234
	v_cvt_f32_ubyte2_e32 v248, v234
	v_pk_mul_f32 v[6:7], v[6:7], v[64:65] op_sel_hi:[1,0]
	v_pk_mul_f32 v[6:7], v[6:7], v[248:249]
	v_cvt_pk_bf16_f32 v0, v0, v1
	v_cvt_pk_bf16_f32 v1, v2, v3
	v_cvt_pk_bf16_f32 v2, v4, v5
	v_cvt_pk_bf16_f32 v3, v6, v7
	s_nop 1
	v_permlane32_swap_b32_e32 v0, v2
	v_permlane32_swap_b32_e32 v1, v3
	global_store_dwordx4 v[56:57], v[0:3], off offset:128
	v_cvt_f32_ubyte1_e32 v249, v235
	v_cvt_f32_ubyte0_e32 v248, v235
	v_pk_mul_f32 v[8:9], v[8:9], v[64:65] op_sel_hi:[1,0]
	v_pk_mul_f32 v[8:9], v[8:9], v[248:249]
	v_cvt_f32_ubyte3_e32 v249, v235
	v_cvt_f32_ubyte2_e32 v248, v235
	v_pk_mul_f32 v[10:11], v[10:11], v[64:65] op_sel_hi:[1,0]
	v_pk_mul_f32 v[10:11], v[10:11], v[248:249]
	v_cvt_f32_ubyte1_e32 v249, v236
	v_cvt_f32_ubyte0_e32 v248, v236
	v_pk_mul_f32 v[12:13], v[12:13], v[64:65] op_sel_hi:[1,0]
	v_pk_mul_f32 v[12:13], v[12:13], v[248:249]
	v_cvt_f32_ubyte3_e32 v249, v236
	v_cvt_f32_ubyte2_e32 v248, v236
	v_pk_mul_f32 v[14:15], v[14:15], v[64:65] op_sel_hi:[1,0]
	v_pk_mul_f32 v[14:15], v[14:15], v[248:249]
	v_cvt_pk_bf16_f32 v8, v8, v9
	v_cvt_pk_bf16_f32 v9, v10, v11
	v_cvt_pk_bf16_f32 v10, v12, v13
	v_cvt_pk_bf16_f32 v11, v14, v15
	s_nop 1
	v_permlane32_swap_b32_e32 v8, v10
	v_permlane32_swap_b32_e32 v9, v11
	global_store_dwordx4 v[56:57], v[8:11], off offset:160
	v_add_u32_e32 v62, 0xc000, v65
	ds_read2_b64 v[0:3], v62 offset0:96 offset1:98
	ds_read2_b64 v[58:61], v62 offset0:100 offset1:102
	s_waitcnt lgkmcnt(1)
	v_mfma_f32_32x32x16_bf16 v[0:15], v[0:3], v[48:51], 0
	ds_read2_b64 v[48:51], v62 offset0:104 offset1:106
	s_waitcnt lgkmcnt(1)
	v_mfma_f32_32x32x16_bf16 v[0:15], v[58:61], v[52:55], v[0:15]
	s_waitcnt lgkmcnt(0)
	v_mfma_f32_32x32x16_bf16 v[0:15], v[48:51], v[24:27], v[0:15]
	ds_read2_b64 v[24:27], v62 offset0:108 offset1:110
	s_waitcnt lgkmcnt(0)
	v_mfma_f32_32x32x16_bf16 v[0:15], v[24:27], v[28:31], v[0:15]
	ds_read2_b64 v[24:27], v62 offset0:112 offset1:114
	s_waitcnt lgkmcnt(0)
	v_mfma_f32_32x32x16_bf16 v[0:15], v[24:27], v[32:35], v[0:15]
	ds_read2_b64 v[24:27], v62 offset0:116 offset1:118
	s_waitcnt lgkmcnt(0)
	v_mfma_f32_32x32x16_bf16 v[0:15], v[24:27], v[36:39], v[0:15]
	ds_read2_b64 v[24:27], v62 offset0:120 offset1:122
	s_waitcnt lgkmcnt(0)
	v_mfma_f32_32x32x16_bf16 v[0:15], v[24:27], v[40:43], v[0:15]
	ds_read2_b64 v[24:27], v62 offset0:124 offset1:126
	s_waitcnt lgkmcnt(0)
	v_mfma_f32_32x32x16_bf16 v[0:15], v[24:27], v[44:47], v[0:15]
	ds_read2_b64 v[24:27], v62 offset0:128 offset1:130
	ds_read2_b64 v[28:31], v62 offset0:132 offset1:134
	s_waitcnt lgkmcnt(1)
	v_mfma_f32_32x32x16_bf16 v[0:15], v[24:27], v[20:23], v[0:15]
	s_waitcnt lgkmcnt(0)
	v_mfma_f32_32x32x16_bf16 v[0:15], v[28:31], v[16:19], v[0:15]
	v_cvt_f32_ubyte1_e32 v249, v237
	v_cvt_f32_ubyte0_e32 v248, v237
	s_nop 9
	v_pk_mul_f32 v[0:1], v[0:1], v[64:65] op_sel_hi:[1,0]
	v_pk_mul_f32 v[0:1], v[0:1], v[248:249]
	v_cvt_f32_ubyte3_e32 v249, v237
	v_cvt_f32_ubyte2_e32 v248, v237
	v_pk_mul_f32 v[2:3], v[2:3], v[64:65] op_sel_hi:[1,0]
	v_pk_mul_f32 v[2:3], v[2:3], v[248:249]
	v_cvt_f32_ubyte1_e32 v249, v238
	v_cvt_f32_ubyte0_e32 v248, v238
	v_pk_mul_f32 v[4:5], v[4:5], v[64:65] op_sel_hi:[1,0]
	v_pk_mul_f32 v[4:5], v[4:5], v[248:249]
	v_cvt_f32_ubyte3_e32 v249, v238
	v_cvt_f32_ubyte2_e32 v248, v238
	v_pk_mul_f32 v[6:7], v[6:7], v[64:65] op_sel_hi:[1,0]
	v_pk_mul_f32 v[6:7], v[6:7], v[248:249]
	v_cvt_pk_bf16_f32 v0, v0, v1
	v_cvt_pk_bf16_f32 v1, v2, v3
	v_cvt_pk_bf16_f32 v2, v4, v5
	v_cvt_pk_bf16_f32 v3, v6, v7
	s_nop 1
	v_permlane32_swap_b32_e32 v0, v2
	v_permlane32_swap_b32_e32 v1, v3
	global_store_dwordx4 v[56:57], v[0:3], off offset:192
	v_cvt_f32_ubyte1_e32 v249, v239
	v_cvt_f32_ubyte0_e32 v248, v239
	v_pk_mul_f32 v[8:9], v[8:9], v[64:65] op_sel_hi:[1,0]
	v_pk_mul_f32 v[8:9], v[8:9], v[248:249]
	v_cvt_f32_ubyte3_e32 v249, v239
	v_cvt_f32_ubyte2_e32 v248, v239
	v_pk_mul_f32 v[10:11], v[10:11], v[64:65] op_sel_hi:[1,0]
	v_pk_mul_f32 v[10:11], v[10:11], v[248:249]
	v_cvt_f32_ubyte1_e32 v249, v240
	v_cvt_f32_ubyte0_e32 v248, v240
	v_pk_mul_f32 v[12:13], v[12:13], v[64:65] op_sel_hi:[1,0]
	v_pk_mul_f32 v[12:13], v[12:13], v[248:249]
	v_cvt_f32_ubyte3_e32 v249, v240
	v_cvt_f32_ubyte2_e32 v248, v240
	v_pk_mul_f32 v[14:15], v[14:15], v[64:65] op_sel_hi:[1,0]
	v_pk_mul_f32 v[14:15], v[14:15], v[248:249]
	v_cvt_pk_bf16_f32 v8, v8, v9
	v_cvt_pk_bf16_f32 v9, v10, v11
	v_cvt_pk_bf16_f32 v10, v12, v13
	v_cvt_pk_bf16_f32 v11, v14, v15
	s_nop 1
	v_permlane32_swap_b32_e32 v8, v10
	v_permlane32_swap_b32_e32 v9, v11
	global_store_dwordx4 v[56:57], v[8:11], off offset:224
	s_cbranch_scc0 .LBB0_400

.LBB0_1598:
	v_ashrrev_i32_e32 v220, 1, v223
	s_lshl_b32 s98, s57, 8
	s_or_b32 s98, s98, s46
	v_and_b32_e32 v220, -8, v220
	v_add_u32_e32 v220, s98, v220
	v_ashrrev_i32_e32 v221, 31, v220
	v_lshl_add_u64 v[220:221], v[220:221], 2, s[10:11]
	global_load_dwordx4 v[204:207], v[220:221], off
	global_load_dwordx4 v[208:211], v[220:221], off offset:16
	global_load_dwordx4 v[212:215], v[220:221], off offset:512
	global_load_dwordx4 v[216:219], v[220:221], off offset:528
	s_add_i32 s47, s47, 1
	s_mul_i32 s4, s47, s75
	s_mul_hi_u32 s5, s47, s74
	s_add_i32 s5, s5, s4
	s_mul_i32 s4, s47, s74
	s_add_u32 s26, s4, s85
	s_addc_u32 s27, s5, s48
	v_cmp_gt_i64_e32 vcc, s[26:27], v[146:147]
	v_cmp_lt_i64_e64 s[4:5], s[26:27], v[144:145]
	s_cbranch_vccnz .LBB0_1604
	s_ashr_i32 s22, s26, 31
	s_lshr_b32 s22, s22, 29
	s_add_i32 s24, s26, s22
	s_and_b32 s22, s24, -8
	s_sub_i32 s25, s26, s22
	s_cmp_gt_i32 s25, -1
	s_mov_b64 s[22:23], -1
	s_cbranch_scc0 .LBB0_1601
	s_lshl_b32 s26, s25, 8
	s_mov_b64 s[22:23], 0

.LBB0_1604:
	s_ashr_i32 s25, s24, 31
	s_lshl_b64 s[26:27], s[24:25], 21
	s_add_u32 s26, s1, s26
	s_addc_u32 s27, s33, s27
	s_and_b64 s[28:29], s[4:5], exec
	s_cselect_b32 s25, s27, s35
	s_cselect_b32 s58, s26, s34
	s_ashr_i32 s23, s22, 31
	s_lshl_b64 s[28:29], s[22:23], 21
	s_add_u32 s28, s44, s28
	s_addc_u32 s29, s45, s29
	s_and_b64 s[38:39], s[4:5], exec
	s_cselect_b32 s23, s29, s37
	s_cselect_b32 s59, s28, s36
	s_add_u32 s60, s36, 0x100
	v_mov_b32_e32 v0, 0
	s_addc_u32 s61, s37, 0
	s_mov_b32 s62, -2
	v_mov_b32_e32 v1, v0
	v_mov_b32_e32 v2, v0
	v_mov_b32_e32 v3, v0
	v_mov_b32_e32 v4, v0
	v_mov_b32_e32 v5, v0
	v_mov_b32_e32 v6, v0
	v_mov_b32_e32 v7, v0
	v_mov_b32_e32 v12, v0
	v_mov_b32_e32 v13, v0
	v_mov_b32_e32 v14, v0
	v_mov_b32_e32 v15, v0
	v_mov_b32_e32 v20, v0
	v_mov_b32_e32 v21, v0
	v_mov_b32_e32 v22, v0
	v_mov_b32_e32 v23, v0
	v_mov_b32_e32 v24, v0
	v_mov_b32_e32 v25, v0
	v_mov_b32_e32 v26, v0
	v_mov_b32_e32 v27, v0
	v_mov_b32_e32 v32, v0
	v_mov_b32_e32 v33, v0
	v_mov_b32_e32 v34, v0
	v_mov_b32_e32 v35, v0
	v_mov_b32_e32 v40, v0
	v_mov_b32_e32 v41, v0
	v_mov_b32_e32 v42, v0
	v_mov_b32_e32 v43, v0
	v_mov_b32_e32 v48, v0
	v_mov_b32_e32 v49, v0
	v_mov_b32_e32 v50, v0
	v_mov_b32_e32 v51, v0
	v_mov_b32_e32 v8, v0
	v_mov_b32_e32 v9, v0
	v_mov_b32_e32 v10, v0
	v_mov_b32_e32 v11, v0
	v_mov_b32_e32 v16, v0
	v_mov_b32_e32 v17, v0
	v_mov_b32_e32 v18, v0
	v_mov_b32_e32 v19, v0
	v_mov_b32_e32 v28, v0
	v_mov_b32_e32 v29, v0
	v_mov_b32_e32 v30, v0
	v_mov_b32_e32 v31, v0
	v_mov_b32_e32 v36, v0
	v_mov_b32_e32 v37, v0
	v_mov_b32_e32 v38, v0
	v_mov_b32_e32 v39, v0
	v_mov_b32_e32 v44, v0
	v_mov_b32_e32 v45, v0
	v_mov_b32_e32 v46, v0
	v_mov_b32_e32 v47, v0
	v_mov_b32_e32 v52, v0
	v_mov_b32_e32 v53, v0
	v_mov_b32_e32 v54, v0
	v_mov_b32_e32 v55, v0
	v_mov_b32_e32 v56, v0
	v_mov_b32_e32 v57, v0
	v_mov_b32_e32 v58, v0
	v_mov_b32_e32 v59, v0
	v_mov_b32_e32 v60, v0
	v_mov_b32_e32 v61, v0
	v_mov_b32_e32 v62, v0
	v_mov_b32_e32 v63, v0
	v_mov_b32_e32 v64, v0
	v_mov_b32_e32 v65, v0
	v_mov_b32_e32 v66, v0
	v_mov_b32_e32 v67, v0
	v_mov_b32_e32 v68, v0
	v_mov_b32_e32 v69, v0
	v_mov_b32_e32 v70, v0
	v_mov_b32_e32 v71, v0
	v_mov_b32_e32 v80, v0
	v_mov_b32_e32 v81, v0
	v_mov_b32_e32 v82, v0
	v_mov_b32_e32 v83, v0
	v_mov_b32_e32 v84, v0
	v_mov_b32_e32 v85, v0
	v_mov_b32_e32 v86, v0
	v_mov_b32_e32 v87, v0
	s_waitcnt vmcnt(1)
	v_mov_b32_e32 v96, v0
	v_mov_b32_e32 v97, v0
	v_mov_b32_e32 v98, v0
	v_mov_b32_e32 v99, v0
	v_mov_b32_e32 v100, v0
	v_mov_b32_e32 v101, v0
	v_mov_b32_e32 v102, v0
	v_mov_b32_e32 v103, v0
	v_mov_b32_e32 v104, v0
	v_mov_b32_e32 v105, v0
	v_mov_b32_e32 v106, v0
	v_mov_b32_e32 v107, v0
	v_mov_b32_e32 v108, v0
	v_mov_b32_e32 v109, v0
	v_mov_b32_e32 v110, v0
	v_mov_b32_e32 v111, v0
	v_mov_b32_e32 v72, v0
	v_mov_b32_e32 v73, v0
	v_mov_b32_e32 v74, v0
	v_mov_b32_e32 v75, v0
	v_mov_b32_e32 v76, v0
	v_mov_b32_e32 v77, v0
	v_mov_b32_e32 v78, v0
	v_mov_b32_e32 v79, v0
	v_mov_b32_e32 v88, v0
	v_mov_b32_e32 v89, v0
	v_mov_b32_e32 v90, v0
	v_mov_b32_e32 v91, v0
	v_mov_b32_e32 v92, v0
	v_mov_b32_e32 v93, v0
	v_mov_b32_e32 v94, v0
	v_mov_b32_e32 v95, v0
	v_mov_b32_e32 v112, v0
	v_mov_b32_e32 v113, v0
	v_mov_b32_e32 v114, v0
	v_mov_b32_e32 v115, v0
	v_mov_b32_e32 v116, v0
	v_mov_b32_e32 v117, v0
	v_mov_b32_e32 v118, v0
	v_mov_b32_e32 v119, v0
	v_mov_b32_e32 v128, v0
	v_mov_b32_e32 v129, v0
	v_mov_b32_e32 v130, v0
	v_mov_b32_e32 v131, v0
	v_mov_b32_e32 v132, v0
	v_mov_b32_e32 v133, v0
	v_mov_b32_e32 v134, v0
	v_mov_b32_e32 v135, v0

.LBB0_1608:
	v_mov_b32_e32 v150, v223
	s_lshl_b32 s23, s57, 8
	v_ashrrev_i32_e32 v120, 1, v150
	s_or_b32 s23, s23, s46
	v_and_b32_e32 v120, -8, v120
	v_add_u32_e32 v148, s23, v120
	v_ashrrev_i32_e32 v149, 31, v148
	v_and_b32_e32 v151, 15, v150
	v_lshlrev_b32_e32 v174, 2, v151
	v_add_u32_e32 v159, s49, v174
	s_lshl_b32 s23, s30, 8
	ds_read2_b32 v[164:165], v159 offset1:16
	s_add_i32 s23, s23, s31
	v_or_b32_e32 v150, s23, v151
	v_ashrrev_i32_e32 v151, 31, v150
	v_lshlrev_b64 v[162:163], 15, v[150:151]
	v_lshl_add_u64 v[162:163], s[8:9], 0, v[162:163]
	v_lshlrev_b64 v[166:167], 1, v[148:149]
	v_lshl_add_u64 v[148:149], v[162:163], 0, v[166:167]
	s_waitcnt lgkmcnt(0)
	v_mov_b32_e32 v162, v165
	v_or_b32_e32 v160, 16, v150
	v_ashrrev_i32_e32 v161, 31, v160
	v_lshlrev_b64 v[160:161], 15, v[160:161]
	v_lshl_add_u64 v[160:161], s[8:9], 0, v[160:161]
	v_lshl_add_u64 v[160:161], v[160:161], 0, v[166:167]
	v_pk_fma_f32 v[134:135], v[134:135], v[164:165], v[206:207] op_sel_hi:[1,0,1]
	v_pk_fma_f32 v[132:133], v[132:133], v[164:165], v[204:205] op_sel_hi:[1,0,1]
	v_pk_fma_f32 v[130:131], v[130:131], v[164:165], v[210:211] op_sel_hi:[1,0,1]
	v_pk_fma_f32 v[128:129], v[128:129], v[164:165], v[208:209] op_sel_hi:[1,0,1]
	v_pk_fma_f32 v[110:111], v[110:111], v[164:165], v[214:215] op_sel_hi:[1,0,1]
	v_pk_fma_f32 v[108:109], v[108:109], v[164:165], v[212:213] op_sel_hi:[1,0,1]
	v_pk_fma_f32 v[106:107], v[106:107], v[164:165], v[218:219] op_sel_hi:[1,0,1]
	v_pk_fma_f32 v[104:105], v[104:105], v[164:165], v[216:217] op_sel_hi:[1,0,1]
	v_max_f32_e32 v132, 0, v132
	v_max_f32_e32 v128, 0, v128
	v_max_f32_e32 v133, 0, v133
	v_max_f32_e32 v129, 0, v129
	v_max_f32_e32 v134, 0, v134
	v_max_f32_e32 v130, 0, v130
	v_max_f32_e32 v135, 0, v135
	v_max_f32_e32 v131, 0, v131
	v_max_f32_e32 v108, 0, v108
	v_max_f32_e32 v104, 0, v104
	v_max_f32_e32 v109, 0, v109
	v_max_f32_e32 v105, 0, v105
	v_max_f32_e32 v110, 0, v110
	v_max_f32_e32 v106, 0, v106
	v_max_f32_e32 v111, 0, v111
	v_max_f32_e32 v107, 0, v107
	v_pk_mul_f32 v[132:133], v[132:133], v[132:133]
	v_pk_mul_f32 v[128:129], v[128:129], v[128:129]
	v_pk_mul_f32 v[134:135], v[134:135], v[134:135]
	v_pk_mul_f32 v[130:131], v[130:131], v[130:131]
	v_pk_fma_f32 v[96:97], v[96:97], v[162:163], v[216:217] op_sel_hi:[1,0,1]
	v_pk_mul_f32 v[108:109], v[108:109], v[108:109]
	v_pk_mul_f32 v[164:165], v[104:105], v[104:105]
	v_pk_mul_f32 v[110:111], v[110:111], v[110:111]
	v_pk_mul_f32 v[168:169], v[106:107], v[106:107]
	v_cvt_pk_bf16_f32 v104, v132, v133
	v_cvt_pk_bf16_f32 v105, v134, v135
	v_cvt_pk_bf16_f32 v106, v128, v129
	v_cvt_pk_bf16_f32 v107, v130, v131
	v_pk_fma_f32 v[102:103], v[102:103], v[162:163], v[214:215] op_sel_hi:[1,0,1]
	v_pk_fma_f32 v[100:101], v[100:101], v[162:163], v[212:213] op_sel_hi:[1,0,1]
	v_pk_fma_f32 v[98:99], v[98:99], v[162:163], v[218:219] op_sel_hi:[1,0,1]
	v_max_f32_e32 v96, 0, v96
	v_max_f32_e32 v97, 0, v97
	v_cvt_pk_bf16_f32 v108, v108, v109
	v_cvt_pk_bf16_f32 v109, v110, v111
	v_cvt_pk_bf16_f32 v110, v164, v165
	v_cvt_pk_bf16_f32 v111, v168, v169
	global_store_dwordx4 v[148:149], v[104:107], off
	global_store_dwordx4 v[148:149], v[108:111], off offset:256
	v_max_f32_e32 v100, 0, v100
	v_max_f32_e32 v101, 0, v101
	v_pk_mul_f32 v[104:105], v[96:97], v[96:97]
	v_max_f32_e32 v96, 0, v102
	v_max_f32_e32 v98, 0, v98
	v_max_f32_e32 v97, 0, v103
	v_max_f32_e32 v99, 0, v99
	v_pk_mul_f32 v[100:101], v[100:101], v[100:101]
	v_pk_mul_f32 v[102:103], v[96:97], v[96:97]
	v_pk_mul_f32 v[106:107], v[98:99], v[98:99]
	v_cvt_pk_bf16_f32 v96, v100, v101
	v_cvt_pk_bf16_f32 v97, v102, v103
	v_cvt_pk_bf16_f32 v98, v104, v105
	v_cvt_pk_bf16_f32 v99, v106, v107
	global_store_dwordx4 v[160:161], v[96:99], off offset:256
	ds_read2_b32 v[98:99], v159 offset0:32 offset1:48
	v_pk_fma_f32 v[118:119], v[118:119], v[162:163], v[206:207] op_sel_hi:[1,0,1]
	v_or_b32_e32 v96, 32, v150
	v_ashrrev_i32_e32 v97, 31, v96
	v_lshlrev_b64 v[96:97], 15, v[96:97]
	s_waitcnt lgkmcnt(0)
	v_pk_fma_f32 v[88:89], v[88:89], v[98:99], v[208:209] op_sel_hi:[1,0,1]
	v_pk_fma_f32 v[94:95], v[94:95], v[98:99], v[206:207] op_sel_hi:[1,0,1]
	v_pk_fma_f32 v[92:93], v[92:93], v[98:99], v[204:205] op_sel_hi:[1,0,1]
	v_pk_fma_f32 v[90:91], v[90:91], v[98:99], v[210:211] op_sel_hi:[1,0,1]
	v_max_f32_e32 v88, 0, v88
	v_max_f32_e32 v89, 0, v89
	v_max_f32_e32 v92, 0, v92
	v_max_f32_e32 v93, 0, v93
	v_pk_mul_f32 v[100:101], v[88:89], v[88:89]
	v_max_f32_e32 v88, 0, v94
	v_max_f32_e32 v90, 0, v90
	v_max_f32_e32 v89, 0, v95
	v_max_f32_e32 v91, 0, v91
	v_lshl_add_u64 v[96:97], s[8:9], 0, v[96:97]
	v_pk_mul_f32 v[92:93], v[92:93], v[92:93]
	v_pk_mul_f32 v[94:95], v[88:89], v[88:89]
	v_pk_mul_f32 v[102:103], v[90:91], v[90:91]
	v_pk_fma_f32 v[80:81], v[80:81], v[98:99], v[216:217] op_sel_hi:[1,0,1]
	v_lshl_add_u64 v[96:97], v[96:97], 0, v[166:167]
	v_cvt_pk_bf16_f32 v88, v92, v93
	v_cvt_pk_bf16_f32 v89, v94, v95
	v_cvt_pk_bf16_f32 v90, v100, v101
	v_cvt_pk_bf16_f32 v91, v102, v103
	v_pk_fma_f32 v[86:87], v[86:87], v[98:99], v[214:215] op_sel_hi:[1,0,1]
	v_pk_fma_f32 v[84:85], v[84:85], v[98:99], v[212:213] op_sel_hi:[1,0,1]
	v_pk_fma_f32 v[82:83], v[82:83], v[98:99], v[218:219] op_sel_hi:[1,0,1]
	v_max_f32_e32 v80, 0, v80
	v_max_f32_e32 v81, 0, v81
	global_store_dwordx4 v[96:97], v[88:91], off
	v_max_f32_e32 v84, 0, v84
	v_max_f32_e32 v85, 0, v85
	v_pk_mul_f32 v[88:89], v[80:81], v[80:81]
	v_max_f32_e32 v80, 0, v86
	v_max_f32_e32 v82, 0, v82
	v_max_f32_e32 v81, 0, v87
	v_max_f32_e32 v83, 0, v83
	v_pk_mul_f32 v[84:85], v[84:85], v[84:85]
	v_pk_mul_f32 v[86:87], v[80:81], v[80:81]
	v_pk_mul_f32 v[90:91], v[82:83], v[82:83]
	v_cvt_pk_bf16_f32 v80, v84, v85
	v_cvt_pk_bf16_f32 v81, v86, v87
	v_cvt_pk_bf16_f32 v82, v88, v89
	v_cvt_pk_bf16_f32 v83, v90, v91
	global_store_dwordx4 v[96:97], v[80:83], off offset:256
	v_pk_fma_f32 v[116:117], v[116:117], v[162:163], v[204:205] op_sel_hi:[1,0,1]
	v_pk_fma_f32 v[114:115], v[114:115], v[162:163], v[210:211] op_sel_hi:[1,0,1]
	v_mov_b32_e32 v82, v99
	v_or_b32_e32 v80, 48, v150
	v_pk_fma_f32 v[72:73], v[72:73], v[82:83], v[208:209] op_sel_hi:[1,0,1]
	v_ashrrev_i32_e32 v81, 31, v80
	v_pk_fma_f32 v[78:79], v[78:79], v[82:83], v[206:207] op_sel_hi:[1,0,1]
	v_pk_fma_f32 v[76:77], v[76:77], v[82:83], v[204:205] op_sel_hi:[1,0,1]
	v_pk_fma_f32 v[74:75], v[74:75], v[82:83], v[210:211] op_sel_hi:[1,0,1]
	v_max_f32_e32 v72, 0, v72
	v_max_f32_e32 v73, 0, v73
	v_pk_fma_f32 v[70:71], v[70:71], v[82:83], v[214:215] op_sel_hi:[1,0,1]
	v_pk_fma_f32 v[68:69], v[68:69], v[82:83], v[212:213] op_sel_hi:[1,0,1]
	v_pk_fma_f32 v[64:65], v[64:65], v[82:83], v[216:217] op_sel_hi:[1,0,1]
	v_lshlrev_b64 v[80:81], 15, v[80:81]
	v_max_f32_e32 v76, 0, v76
	v_max_f32_e32 v77, 0, v77
	v_pk_mul_f32 v[84:85], v[72:73], v[72:73]
	v_max_f32_e32 v72, 0, v78
	v_max_f32_e32 v74, 0, v74
	v_max_f32_e32 v73, 0, v79
	v_max_f32_e32 v75, 0, v75
	v_max_f32_e32 v68, 0, v68
	v_max_f32_e32 v64, 0, v64
	v_max_f32_e32 v69, 0, v69
	v_max_f32_e32 v65, 0, v65
	v_max_f32_e32 v70, 0, v70
	v_max_f32_e32 v71, 0, v71
	v_lshl_add_u64 v[80:81], s[8:9], 0, v[80:81]
	v_pk_mul_f32 v[76:77], v[76:77], v[76:77]
	v_pk_mul_f32 v[78:79], v[72:73], v[72:73]
	v_pk_mul_f32 v[86:87], v[74:75], v[74:75]
	v_pk_fma_f32 v[66:67], v[66:67], v[82:83], v[218:219] op_sel_hi:[1,0,1]
	v_pk_mul_f32 v[68:69], v[68:69], v[68:69]
	v_pk_mul_f32 v[64:65], v[64:65], v[64:65]
	v_pk_mul_f32 v[70:71], v[70:71], v[70:71]
	v_lshl_add_u64 v[80:81], v[80:81], 0, v[166:167]
	v_cvt_pk_bf16_f32 v72, v76, v77
	v_cvt_pk_bf16_f32 v73, v78, v79
	v_cvt_pk_bf16_f32 v74, v84, v85
	v_cvt_pk_bf16_f32 v75, v86, v87
	v_max_f32_e32 v66, 0, v66
	v_max_f32_e32 v67, 0, v67
	v_cvt_pk_bf16_f32 v68, v68, v69
	v_cvt_pk_bf16_f32 v69, v70, v71
	v_cvt_pk_bf16_f32 v70, v64, v65
	v_add_u32_e32 v64, s50, v174
	global_store_dwordx4 v[80:81], v[72:75], off
	v_pk_fma_f32 v[112:113], v[112:113], v[162:163], v[208:209] op_sel_hi:[1,0,1]
	v_max_f32_e32 v116, 0, v116
	v_pk_mul_f32 v[72:73], v[66:67], v[66:67]
	ds_read_b32 v66, v64
	v_cvt_pk_bf16_f32 v71, v72, v73
	global_store_dwordx4 v[80:81], v[68:71], off offset:256
	ds_read_b32 v68, v159 offset:704
	v_lshl_add_u64 v[64:65], v[148:149], 0, s[14:15]
	s_waitcnt lgkmcnt(1)
	v_pk_fma_f32 v[60:61], v[60:61], v[66:67], v[204:205] op_sel_hi:[1,0,1]
	v_pk_fma_f32 v[56:57], v[56:57], v[66:67], v[208:209] op_sel_hi:[1,0,1]
	v_pk_fma_f32 v[62:63], v[62:63], v[66:67], v[206:207] op_sel_hi:[1,0,1]
	v_pk_fma_f32 v[58:59], v[58:59], v[66:67], v[210:211] op_sel_hi:[1,0,1]
	v_max_f32_e32 v60, 0, v60
	v_max_f32_e32 v56, 0, v56
	v_max_f32_e32 v61, 0, v61
	v_max_f32_e32 v57, 0, v57
	v_pk_mul_f32 v[60:61], v[60:61], v[60:61]
	v_pk_mul_f32 v[70:71], v[56:57], v[56:57]
	v_max_f32_e32 v56, 0, v62
	v_max_f32_e32 v58, 0, v58
	v_max_f32_e32 v57, 0, v63
	v_max_f32_e32 v59, 0, v59
	v_pk_mul_f32 v[62:63], v[56:57], v[56:57]
	v_pk_mul_f32 v[72:73], v[58:59], v[58:59]
	v_cvt_pk_bf16_f32 v56, v60, v61
	v_add_co_u32_e32 v60, vcc, s51, v148
	v_pk_fma_f32 v[48:49], v[48:49], v[66:67], v[212:213] op_sel_hi:[1,0,1]
	v_pk_fma_f32 v[40:41], v[40:41], v[66:67], v[216:217] op_sel_hi:[1,0,1]
	v_cvt_pk_bf16_f32 v57, v62, v63
	v_cvt_pk_bf16_f32 v58, v70, v71
	v_cvt_pk_bf16_f32 v59, v72, v73
	v_addc_co_u32_e32 v61, vcc, 0, v149, vcc
	v_pk_fma_f32 v[50:51], v[50:51], v[66:67], v[214:215] op_sel_hi:[1,0,1]
	v_max_f32_e32 v48, 0, v48
	v_max_f32_e32 v40, 0, v40
	v_max_f32_e32 v49, 0, v49
	v_max_f32_e32 v41, 0, v41
	global_store_dwordx4 v[60:61], v[56:59], off
	v_pk_mul_f32 v[48:49], v[48:49], v[48:49]
	v_pk_fma_f32 v[42:43], v[42:43], v[66:67], v[218:219] op_sel_hi:[1,0,1]
	v_pk_mul_f32 v[56:57], v[40:41], v[40:41]
	v_max_f32_e32 v40, 0, v50
	v_max_f32_e32 v41, 0, v51
	v_pk_mul_f32 v[50:51], v[40:41], v[40:41]
	v_cvt_pk_bf16_f32 v40, v48, v49
	ds_read2_b32 v[48:49], v159 offset0:144 offset1:160
	v_max_f32_e32 v42, 0, v42
	v_max_f32_e32 v43, 0, v43
	v_pk_mul_f32 v[58:59], v[42:43], v[42:43]
	v_cvt_pk_bf16_f32 v41, v50, v51
	v_cvt_pk_bf16_f32 v42, v56, v57
	v_cvt_pk_bf16_f32 v43, v58, v59
	global_store_dwordx4 v[64:65], v[40:43], off offset:256
	s_waitcnt lgkmcnt(0)
	v_pk_fma_f32 v[44:45], v[44:45], v[48:49], v[208:209] op_sel_hi:[1,0,1]
	v_pk_fma_f32 v[46:47], v[46:47], v[48:49], v[210:211] op_sel_hi:[1,0,1]
	v_pk_fma_f32 v[42:43], v[52:53], v[48:49], v[204:205] op_sel_hi:[1,0,1]
	v_pk_fma_f32 v[40:41], v[54:55], v[48:49], v[206:207] op_sel_hi:[1,0,1]
	v_max_f32_e32 v42, 0, v42
	v_max_f32_e32 v44, 0, v44
	v_max_f32_e32 v43, 0, v43
	v_max_f32_e32 v45, 0, v45
	v_pk_mul_f32 v[42:43], v[42:43], v[42:43]
	v_pk_mul_f32 v[44:45], v[44:45], v[44:45]
	v_max_f32_e32 v40, 0, v40
	v_max_f32_e32 v46, 0, v46
	v_max_f32_e32 v41, 0, v41
	v_max_f32_e32 v47, 0, v47
	v_pk_mul_f32 v[52:53], v[40:41], v[40:41]
	v_pk_mul_f32 v[46:47], v[46:47], v[46:47]
	v_cvt_pk_bf16_f32 v40, v42, v43
	v_cvt_pk_bf16_f32 v42, v44, v45
	v_add_co_u32_e32 v44, vcc, s52, v148
	v_pk_fma_f32 v[24:25], v[24:25], v[48:49], v[216:217] op_sel_hi:[1,0,1]
	v_cvt_pk_bf16_f32 v41, v52, v53
	v_cvt_pk_bf16_f32 v43, v46, v47
	v_addc_co_u32_e32 v45, vcc, 0, v149, vcc
	v_pk_fma_f32 v[34:35], v[34:35], v[48:49], v[214:215] op_sel_hi:[1,0,1]
	v_pk_fma_f32 v[32:33], v[32:33], v[48:49], v[212:213] op_sel_hi:[1,0,1]
	v_pk_fma_f32 v[26:27], v[26:27], v[48:49], v[218:219] op_sel_hi:[1,0,1]
	v_max_f32_e32 v24, 0, v24
	v_max_f32_e32 v25, 0, v25
	global_store_dwordx4 v[44:45], v[40:43], off
	v_max_f32_e32 v32, 0, v32
	v_max_f32_e32 v33, 0, v33
	v_pk_mul_f32 v[40:41], v[24:25], v[24:25]
	v_max_f32_e32 v24, 0, v34
	v_max_f32_e32 v26, 0, v26
	v_max_f32_e32 v25, 0, v35
	v_max_f32_e32 v27, 0, v27
	v_pk_mul_f32 v[32:33], v[32:33], v[32:33]
	v_pk_mul_f32 v[34:35], v[24:25], v[24:25]
	v_pk_mul_f32 v[42:43], v[26:27], v[26:27]
	v_lshl_add_u64 v[50:51], v[148:149], 0, s[16:17]
	v_cvt_pk_bf16_f32 v24, v32, v33
	v_cvt_pk_bf16_f32 v25, v34, v35
	v_cvt_pk_bf16_f32 v26, v40, v41
	v_cvt_pk_bf16_f32 v27, v42, v43
	v_mov_b32_e32 v34, v49
	global_store_dwordx4 v[50:51], v[24:27], off offset:256
	v_pk_fma_f32 v[28:29], v[28:29], v[34:35], v[208:209] op_sel_hi:[1,0,1]
	v_pk_fma_f32 v[30:31], v[30:31], v[34:35], v[210:211] op_sel_hi:[1,0,1]
	v_pk_fma_f32 v[26:27], v[36:37], v[34:35], v[204:205] op_sel_hi:[1,0,1]
	v_pk_fma_f32 v[24:25], v[38:39], v[34:35], v[206:207] op_sel_hi:[1,0,1]
	v_max_f32_e32 v26, 0, v26
	v_max_f32_e32 v28, 0, v28
	v_max_f32_e32 v27, 0, v27
	v_max_f32_e32 v29, 0, v29
	v_pk_mul_f32 v[26:27], v[26:27], v[26:27]
	v_pk_mul_f32 v[28:29], v[28:29], v[28:29]
	v_max_f32_e32 v24, 0, v24
	v_max_f32_e32 v30, 0, v30
	v_max_f32_e32 v25, 0, v25
	v_max_f32_e32 v31, 0, v31
	v_pk_mul_f32 v[36:37], v[24:25], v[24:25]
	v_pk_mul_f32 v[30:31], v[30:31], v[30:31]
	v_cvt_pk_bf16_f32 v24, v26, v27
	v_cvt_pk_bf16_f32 v26, v28, v29
	v_add_co_u32_e32 v28, vcc, s53, v148
	v_pk_fma_f32 v[12:13], v[12:13], v[34:35], v[216:217] op_sel_hi:[1,0,1]
	v_cvt_pk_bf16_f32 v25, v36, v37
	v_cvt_pk_bf16_f32 v27, v30, v31
	v_addc_co_u32_e32 v29, vcc, 0, v149, vcc
	v_pk_fma_f32 v[22:23], v[22:23], v[34:35], v[214:215] op_sel_hi:[1,0,1]
	v_pk_fma_f32 v[20:21], v[20:21], v[34:35], v[212:213] op_sel_hi:[1,0,1]
	v_pk_fma_f32 v[14:15], v[14:15], v[34:35], v[218:219] op_sel_hi:[1,0,1]
	v_max_f32_e32 v12, 0, v12
	v_max_f32_e32 v13, 0, v13
	global_store_dwordx4 v[28:29], v[24:27], off
	v_max_f32_e32 v20, 0, v20
	v_max_f32_e32 v21, 0, v21
	v_pk_mul_f32 v[24:25], v[12:13], v[12:13]
	v_max_f32_e32 v12, 0, v22
	v_max_f32_e32 v14, 0, v14
	v_max_f32_e32 v13, 0, v23
	v_max_f32_e32 v15, 0, v15
	v_pk_mul_f32 v[20:21], v[20:21], v[20:21]
	v_pk_mul_f32 v[22:23], v[12:13], v[12:13]
	v_pk_mul_f32 v[26:27], v[14:15], v[14:15]
	v_lshl_add_u64 v[32:33], v[148:149], 0, s[18:19]
	v_cvt_pk_bf16_f32 v12, v20, v21
	v_cvt_pk_bf16_f32 v13, v22, v23
	v_cvt_pk_bf16_f32 v14, v24, v25
	v_cvt_pk_bf16_f32 v15, v26, v27
	v_pk_fma_f32 v[8:9], v[8:9], v[68:69], v[208:209] op_sel_hi:[1,0,1]
	global_store_dwordx4 v[32:33], v[12:15], off offset:256
	v_max_f32_e32 v8, 0, v8
	v_max_f32_e32 v9, 0, v9
	v_pk_fma_f32 v[14:15], v[18:19], v[68:69], v[206:207] op_sel_hi:[1,0,1]
	v_pk_fma_f32 v[16:17], v[16:17], v[68:69], v[204:205] op_sel_hi:[1,0,1]
	v_pk_fma_f32 v[10:11], v[10:11], v[68:69], v[210:211] op_sel_hi:[1,0,1]
	v_pk_mul_f32 v[18:19], v[8:9], v[8:9]
	v_max_f32_e32 v8, 0, v14
	v_max_f32_e32 v9, 0, v15
	v_max_f32_e32 v16, 0, v16
	v_max_f32_e32 v17, 0, v17
	v_max_f32_e32 v10, 0, v10
	v_max_f32_e32 v11, 0, v11
	v_pk_mul_f32 v[14:15], v[8:9], v[8:9]
	v_pk_mul_f32 v[16:17], v[16:17], v[16:17]
	v_pk_mul_f32 v[20:21], v[10:11], v[10:11]
	v_cvt_pk_bf16_f32 v9, v14, v15
	v_add_co_u32_e32 v14, vcc, s56, v148
	v_pk_fma_f32 v[0:1], v[0:1], v[68:69], v[216:217] op_sel_hi:[1,0,1]
	v_cvt_pk_bf16_f32 v8, v16, v17
	v_cvt_pk_bf16_f32 v10, v18, v19
	v_cvt_pk_bf16_f32 v11, v20, v21
	v_addc_co_u32_e32 v15, vcc, 0, v149, vcc
	v_pk_fma_f32 v[6:7], v[6:7], v[68:69], v[214:215] op_sel_hi:[1,0,1]
	v_pk_fma_f32 v[4:5], v[4:5], v[68:69], v[212:213] op_sel_hi:[1,0,1]
	v_pk_fma_f32 v[2:3], v[2:3], v[68:69], v[218:219] op_sel_hi:[1,0,1]
	v_max_f32_e32 v0, 0, v0
	v_max_f32_e32 v1, 0, v1
	v_max_f32_e32 v112, 0, v112
	v_max_f32_e32 v117, 0, v117
	v_max_f32_e32 v113, 0, v113
	v_max_f32_e32 v118, 0, v118
	v_max_f32_e32 v114, 0, v114
	v_max_f32_e32 v119, 0, v119
	v_max_f32_e32 v115, 0, v115
	global_store_dwordx4 v[14:15], v[8:11], off
	v_max_f32_e32 v4, 0, v4
	v_max_f32_e32 v5, 0, v5
	v_pk_mul_f32 v[8:9], v[0:1], v[0:1]
	v_max_f32_e32 v0, 0, v6
	v_max_f32_e32 v2, 0, v2
	v_max_f32_e32 v1, 0, v7
	v_max_f32_e32 v3, 0, v3
	v_pk_mul_f32 v[116:117], v[116:117], v[116:117]
	v_pk_mul_f32 v[170:171], v[112:113], v[112:113]
	v_pk_mul_f32 v[118:119], v[118:119], v[118:119]
	v_pk_mul_f32 v[172:173], v[114:115], v[114:115]
	v_pk_mul_f32 v[4:5], v[4:5], v[4:5]
	v_pk_mul_f32 v[6:7], v[0:1], v[0:1]
	v_pk_mul_f32 v[10:11], v[2:3], v[2:3]
	v_cvt_pk_bf16_f32 v112, v116, v117
	v_cvt_pk_bf16_f32 v113, v118, v119
	v_cvt_pk_bf16_f32 v114, v170, v171
	v_cvt_pk_bf16_f32 v115, v172, v173
	v_lshl_add_u64 v[12:13], v[148:149], 0, s[20:21]
	v_cvt_pk_bf16_f32 v0, v4, v5
	v_cvt_pk_bf16_f32 v1, v6, v7
	v_cvt_pk_bf16_f32 v2, v8, v9
	v_cvt_pk_bf16_f32 v3, v10, v11
	s_andn2_b64 vcc, exec, s[4:5]
	s_mov_b64 s[4:5], -1
	global_store_dwordx4 v[160:161], v[112:115], off
	global_store_dwordx4 v[12:13], v[0:3], off offset:256
	s_cbranch_vccnz .LBB0_1597
	s_andn2_b64 vcc, exec, s[6:7]
	s_cbranch_vccnz .LBB0_1596
	s_barrier
	s_branch .LBB0_1596

	.amdhsa_kernel _Z6mk_fwd4Args
		.amdhsa_group_segment_fixed_size 0
		.amdhsa_private_segment_fixed_size 0
		.amdhsa_kernarg_size 456
		.amdhsa_user_sgpr_count 2
		.amdhsa_user_sgpr_dispatch_ptr 0
		.amdhsa_user_sgpr_queue_ptr 0
		.amdhsa_user_sgpr_kernarg_segment_ptr 1
		.amdhsa_user_sgpr_dispatch_id 0
		.amdhsa_user_sgpr_kernarg_preload_length 0
		.amdhsa_user_sgpr_kernarg_preload_offset 0
		.amdhsa_user_sgpr_private_segment_size 0
		.amdhsa_uses_dynamic_stack 0
		.amdhsa_enable_private_segment 0
		.amdhsa_system_sgpr_workgroup_id_x 1
		.amdhsa_system_sgpr_workgroup_id_y 0
		.amdhsa_system_sgpr_workgroup_id_z 0
		.amdhsa_system_sgpr_workgroup_info 0
		.amdhsa_system_vgpr_workitem_id 0
		.amdhsa_next_free_vgpr 251
		.amdhsa_next_free_sgpr 100
		.amdhsa_accum_offset 252
		.amdhsa_reserve_vcc 1
		.amdhsa_float_round_mode_32 0
		.amdhsa_float_round_mode_16_64 0
		.amdhsa_float_denorm_mode_32 3
		.amdhsa_float_denorm_mode_16_64 3
		.amdhsa_dx10_clamp 1
		.amdhsa_ieee_mode 1
		.amdhsa_fp16_overflow 0
		.amdhsa_tg_split 0
		.amdhsa_exception_fp_ieee_invalid_op 0
		.amdhsa_exception_fp_denorm_src 0
		.amdhsa_exception_fp_ieee_div_zero 0
		.amdhsa_exception_fp_ieee_overflow 0
		.amdhsa_exception_fp_ieee_underflow 0
		.amdhsa_exception_fp_ieee_inexact 0
		.amdhsa_exception_int_div_zero 0
	.end_amdhsa_kernel

amdhsa.kernels:
  - .agpr_count:     0
    .args:
      - .offset:         0
        .size:           200
        .value_kind:     by_value
      - .offset:         200
        .size:           4
        .value_kind:     hidden_block_count_x
      - .offset:         204
        .size:           4
        .value_kind:     hidden_block_count_y
      - .offset:         208
        .size:           4
        .value_kind:     hidden_block_count_z
      - .offset:         212
        .size:           2
        .value_kind:     hidden_group_size_x
      - .offset:         214
        .size:           2
        .value_kind:     hidden_group_size_y
      - .offset:         216
        .size:           2
        .value_kind:     hidden_group_size_z
      - .offset:         218
        .size:           2
        .value_kind:     hidden_remainder_x
      - .offset:         220
        .size:           2
        .value_kind:     hidden_remainder_y
      - .offset:         222
        .size:           2
        .value_kind:     hidden_remainder_z
      - .offset:         240
        .size:           8
        .value_kind:     hidden_global_offset_x
      - .offset:         248
        .size:           8
        .value_kind:     hidden_global_offset_y
      - .offset:         256
        .size:           8
        .value_kind:     hidden_global_offset_z
      - .offset:         264
        .size:           2
        .value_kind:     hidden_grid_dims
      - .offset:         320
        .size:           4
        .value_kind:     hidden_dynamic_lds_size
    .group_segment_fixed_size: 0
    .kernarg_segment_align: 8
    .kernarg_segment_size: 456
    .language:       OpenCL C
    .language_version:
      - 2
      - 0
    .max_flat_workgroup_size: 512
    .name:           _Z6mk_fwd4Args
    .private_segment_fixed_size: 0
    .sgpr_count:     106
    .sgpr_spill_count: 21
    .symbol:         _Z6mk_fwd4Args.kd
    .uniform_work_group_size: 1
    .uses_dynamic_stack: false
    .vgpr_count:     251
    .vgpr_spill_count: 0
    .wavefront_size: 64
